# GEMM1 SwiGLU epilogue rewritten: same per-element operations and order, plain multiplies and the add as packed f32 pairs, stage-wise emission
# speedup vs baseline: 1.0314x; 1.0087x over previous
; __device__ __forceinline__ unsigned cvt_pk_bf16(float lo, float hi) { unsigned r; asm volatile("v_cvt_pk_bf16_f32 %0, %1, %2" : "=v"(r) : "v"(lo), "v"(hi)); return r; }
; __device__ __forceinline__ float frcp(float x) { return __builtin_amdgcn_rcpf(x); }
;     __device__ __forceinline__ void operator()(const f32x4 (&acc)[2][2][4][2], const pg8::Unit& u, int wr, int wc, int fr, int fq) const {
;         const int row0 = u.pm * 256 + wr * 64 + fr, col0 = u.pn * 128 + wc * 32 + 8 * fq;
; #pragma unroll
;         for (int ai = 0; ai < 2; ++ai)
; #pragma unroll
;             for (int m = 0; m < 4; ++m) {
;                 bf16* rowp = O + (size_t)(row0 + ai * 128 + m * 16) * FF + col0;
;                 float r[8];
; #pragma unroll
;                 for (int n = 0; n < 2; ++n)
; #pragma unroll
;                     for (int i = 0; i < 4; ++i) { const float g = acc[ai][0][m][n][i], up = acc[ai][1][m][n][i]; r[n * 4 + i] = g * up * frcp(1.f + __expf(-g)); }
;                 u32x4 w; w.x = pg8::cvt_pk_bf16(r[0], r[1]); w.y = pg8::cvt_pk_bf16(r[2], r[3]); w.z = pg8::cvt_pk_bf16(r[4], r[5]); w.w = pg8::cvt_pk_bf16(r[6], r[7]);
;                 *(u32x4*)rowp = w;
;             }
;     }
.LBB0_843:
	v_readlane_b32 s0, v254, 55
	v_readlane_b32 s1, v254, 56
	v_lshl_or_b32 v146, s34, 7, v142
	v_lshl_add_u32 v144, s35, 8, v140
	v_ashrrev_i32_e32 v147, 31, v146
	v_mov_b32_e32 v168, 0xbfb8aa3b
	v_mov_b32_e32 v169, 0xbfb8aa3b
	v_mov_b32_e32 v170, 1.0
	v_mov_b32_e32 v171, 1.0
	v_mov_b64_e32 v[138:139], s[0:1]
	v_lshlrev_b64 v[180:181], 1, v[146:147]
	v_pk_mul_f32 v[124:125], v[124:125], v[120:121]
	v_pk_mul_f32 v[126:127], v[126:127], v[122:123]
	v_pk_mul_f32 v[116:117], v[116:117], v[112:113]
	v_pk_mul_f32 v[118:119], v[118:119], v[114:115]
	v_pk_mul_f32 v[120:121], v[120:121], v[168:169]
	v_pk_mul_f32 v[122:123], v[122:123], v[168:169]
	v_pk_mul_f32 v[112:113], v[112:113], v[168:169]
	v_pk_mul_f32 v[114:115], v[114:115], v[168:169]
	v_exp_f32_e32 v120, v120
	v_exp_f32_e32 v121, v121
	v_exp_f32_e32 v122, v122
	v_exp_f32_e32 v123, v123
	v_exp_f32_e32 v112, v112
	v_exp_f32_e32 v113, v113
	v_exp_f32_e32 v114, v114
	v_exp_f32_e32 v115, v115
	v_or_b32_e32 v186, 0, v144
	v_pk_add_f32 v[120:121], v[120:121], v[170:171]
	v_pk_add_f32 v[122:123], v[122:123], v[170:171]
	v_pk_add_f32 v[112:113], v[112:113], v[170:171]
	v_pk_add_f32 v[114:115], v[114:115], v[170:171]
	v_rcp_f32_e32 v120, v120
	v_rcp_f32_e32 v121, v121
	v_rcp_f32_e32 v122, v122
	v_rcp_f32_e32 v123, v123
	v_rcp_f32_e32 v112, v112
	v_rcp_f32_e32 v113, v113
	v_rcp_f32_e32 v114, v114
	v_rcp_f32_e32 v115, v115
	v_mad_i64_i32 v[182:183], s[0:1], v186, s80, v[138:139]
	s_nop 0
	v_pk_mul_f32 v[124:125], v[124:125], v[120:121]
	v_pk_mul_f32 v[126:127], v[126:127], v[122:123]
	v_pk_mul_f32 v[116:117], v[116:117], v[112:113]
	v_pk_mul_f32 v[118:119], v[118:119], v[114:115]
	v_lshl_add_u64 v[184:185], v[182:183], 0, v[180:181]
	v_cvt_pk_bf16_f32 v172, v124, v125
	v_cvt_pk_bf16_f32 v173, v126, v127
	v_cvt_pk_bf16_f32 v174, v116, v117
	v_cvt_pk_bf16_f32 v175, v118, v119
	global_store_dwordx4 v[184:185], v[172:175], off
	v_pk_mul_f32 v[108:109], v[108:109], v[104:105]
	v_pk_mul_f32 v[110:111], v[110:111], v[106:107]
	v_pk_mul_f32 v[100:101], v[100:101], v[96:97]
	v_pk_mul_f32 v[102:103], v[102:103], v[98:99]
	v_pk_mul_f32 v[104:105], v[104:105], v[168:169]
	v_pk_mul_f32 v[106:107], v[106:107], v[168:169]
	v_pk_mul_f32 v[96:97], v[96:97], v[168:169]
	v_pk_mul_f32 v[98:99], v[98:99], v[168:169]
	v_exp_f32_e32 v104, v104
	v_exp_f32_e32 v105, v105
	v_exp_f32_e32 v106, v106
	v_exp_f32_e32 v107, v107
	v_exp_f32_e32 v96, v96
	v_exp_f32_e32 v97, v97
	v_exp_f32_e32 v98, v98
	v_exp_f32_e32 v99, v99
	v_or_b32_e32 v186, 16, v144
	v_pk_add_f32 v[104:105], v[104:105], v[170:171]
	v_pk_add_f32 v[106:107], v[106:107], v[170:171]
	v_pk_add_f32 v[96:97], v[96:97], v[170:171]
	v_pk_add_f32 v[98:99], v[98:99], v[170:171]
	v_rcp_f32_e32 v104, v104
	v_rcp_f32_e32 v105, v105
	v_rcp_f32_e32 v106, v106
	v_rcp_f32_e32 v107, v107
	v_rcp_f32_e32 v96, v96
	v_rcp_f32_e32 v97, v97
	v_rcp_f32_e32 v98, v98
	v_rcp_f32_e32 v99, v99
	v_mad_i64_i32 v[182:183], s[0:1], v186, s80, v[138:139]
	s_nop 0
	v_pk_mul_f32 v[108:109], v[108:109], v[104:105]
	v_pk_mul_f32 v[110:111], v[110:111], v[106:107]
	v_pk_mul_f32 v[100:101], v[100:101], v[96:97]
	v_pk_mul_f32 v[102:103], v[102:103], v[98:99]
	v_lshl_add_u64 v[184:185], v[182:183], 0, v[180:181]
	v_cvt_pk_bf16_f32 v176, v108, v109
	v_cvt_pk_bf16_f32 v177, v110, v111
	v_cvt_pk_bf16_f32 v178, v100, v101
	v_cvt_pk_bf16_f32 v179, v102, v103
	global_store_dwordx4 v[184:185], v[176:179], off
	v_pk_mul_f32 v[92:93], v[92:93], v[88:89]
	v_pk_mul_f32 v[94:95], v[94:95], v[90:91]
	v_pk_mul_f32 v[84:85], v[84:85], v[80:81]
	v_pk_mul_f32 v[86:87], v[86:87], v[82:83]
	v_pk_mul_f32 v[88:89], v[88:89], v[168:169]
	v_pk_mul_f32 v[90:91], v[90:91], v[168:169]
	v_pk_mul_f32 v[80:81], v[80:81], v[168:169]
	v_pk_mul_f32 v[82:83], v[82:83], v[168:169]
	v_exp_f32_e32 v88, v88
	v_exp_f32_e32 v89, v89
	v_exp_f32_e32 v90, v90
	v_exp_f32_e32 v91, v91
	v_exp_f32_e32 v80, v80
	v_exp_f32_e32 v81, v81
	v_exp_f32_e32 v82, v82
	v_exp_f32_e32 v83, v83
	v_or_b32_e32 v186, 32, v144
	v_pk_add_f32 v[88:89], v[88:89], v[170:171]
	v_pk_add_f32 v[90:91], v[90:91], v[170:171]
	v_pk_add_f32 v[80:81], v[80:81], v[170:171]
	v_pk_add_f32 v[82:83], v[82:83], v[170:171]
	v_rcp_f32_e32 v88, v88
	v_rcp_f32_e32 v89, v89
	v_rcp_f32_e32 v90, v90
	v_rcp_f32_e32 v91, v91
	v_rcp_f32_e32 v80, v80
	v_rcp_f32_e32 v81, v81
	v_rcp_f32_e32 v82, v82
	v_rcp_f32_e32 v83, v83
	v_mad_i64_i32 v[182:183], s[0:1], v186, s80, v[138:139]
	s_nop 0
	v_pk_mul_f32 v[92:93], v[92:93], v[88:89]
	v_pk_mul_f32 v[94:95], v[94:95], v[90:91]
	v_pk_mul_f32 v[84:85], v[84:85], v[80:81]
	v_pk_mul_f32 v[86:87], v[86:87], v[82:83]
	v_lshl_add_u64 v[184:185], v[182:183], 0, v[180:181]
	v_cvt_pk_bf16_f32 v172, v92, v93
	v_cvt_pk_bf16_f32 v173, v94, v95
	v_cvt_pk_bf16_f32 v174, v84, v85
	v_cvt_pk_bf16_f32 v175, v86, v87
	global_store_dwordx4 v[184:185], v[172:175], off
	v_pk_mul_f32 v[76:77], v[76:77], v[72:73]
	v_pk_mul_f32 v[78:79], v[78:79], v[74:75]
	v_pk_mul_f32 v[68:69], v[68:69], v[64:65]
	v_pk_mul_f32 v[70:71], v[70:71], v[66:67]
	v_pk_mul_f32 v[72:73], v[72:73], v[168:169]
	v_pk_mul_f32 v[74:75], v[74:75], v[168:169]
	v_pk_mul_f32 v[64:65], v[64:65], v[168:169]
	v_pk_mul_f32 v[66:67], v[66:67], v[168:169]
	v_exp_f32_e32 v72, v72
	v_exp_f32_e32 v73, v73
	v_exp_f32_e32 v74, v74
	v_exp_f32_e32 v75, v75
	v_exp_f32_e32 v64, v64
	v_exp_f32_e32 v65, v65
	v_exp_f32_e32 v66, v66
	v_exp_f32_e32 v67, v67
	v_or_b32_e32 v186, 48, v144
	v_pk_add_f32 v[72:73], v[72:73], v[170:171]
	v_pk_add_f32 v[74:75], v[74:75], v[170:171]
	v_pk_add_f32 v[64:65], v[64:65], v[170:171]
	v_pk_add_f32 v[66:67], v[66:67], v[170:171]
	v_rcp_f32_e32 v72, v72
	v_rcp_f32_e32 v73, v73
; __device__ __forceinline__ unsigned cvt_pk_bf16(float lo, float hi) { unsigned r; asm volatile("v_cvt_pk_bf16_f32 %0, %1, %2" : "=v"(r) : "v"(lo), "v"(hi)); return r; }
; __device__ __forceinline__ float frcp(float x) { return __builtin_amdgcn_rcpf(x); }
;     __device__ __forceinline__ void operator()(const f32x4 (&acc)[2][2][4][2], const pg8::Unit& u, int wr, int wc, int fr, int fq) const {
;         const int row0 = u.pm * 256 + wr * 64 + fr, col0 = u.pn * 128 + wc * 32 + 8 * fq;
; #pragma unroll
;         for (int ai = 0; ai < 2; ++ai)
; #pragma unroll
;             for (int m = 0; m < 4; ++m) {
;                 bf16* rowp = O + (size_t)(row0 + ai * 128 + m * 16) * FF + col0;
;                 float r[8];
; #pragma unroll
;                 for (int n = 0; n < 2; ++n)
; #pragma unroll
;                     for (int i = 0; i < 4; ++i) { const float g = acc[ai][0][m][n][i], up = acc[ai][1][m][n][i]; r[n * 4 + i] = g * up * frcp(1.f + __expf(-g)); }
;                 u32x4 w; w.x = pg8::cvt_pk_bf16(r[0], r[1]); w.y = pg8::cvt_pk_bf16(r[2], r[3]); w.z = pg8::cvt_pk_bf16(r[4], r[5]); w.w = pg8::cvt_pk_bf16(r[6], r[7]);
;                 *(u32x4*)rowp = w;
;             }
;     }
	v_rcp_f32_e32 v74, v74
	v_rcp_f32_e32 v75, v75
	v_rcp_f32_e32 v64, v64
	v_rcp_f32_e32 v65, v65
	v_rcp_f32_e32 v66, v66
	v_rcp_f32_e32 v67, v67
	v_mad_i64_i32 v[182:183], s[0:1], v186, s80, v[138:139]
	s_nop 0
	v_pk_mul_f32 v[76:77], v[76:77], v[72:73]
	v_pk_mul_f32 v[78:79], v[78:79], v[74:75]
	v_pk_mul_f32 v[68:69], v[68:69], v[64:65]
	v_pk_mul_f32 v[70:71], v[70:71], v[66:67]
	v_lshl_add_u64 v[184:185], v[182:183], 0, v[180:181]
	v_cvt_pk_bf16_f32 v176, v76, v77
	v_cvt_pk_bf16_f32 v177, v78, v79
	v_cvt_pk_bf16_f32 v178, v68, v69
	v_cvt_pk_bf16_f32 v179, v70, v71
	global_store_dwordx4 v[184:185], v[176:179], off
	v_pk_mul_f32 v[60:61], v[60:61], v[56:57]
	v_pk_mul_f32 v[62:63], v[62:63], v[58:59]
	v_pk_mul_f32 v[52:53], v[52:53], v[48:49]
	v_pk_mul_f32 v[54:55], v[54:55], v[50:51]
	v_pk_mul_f32 v[56:57], v[56:57], v[168:169]
	v_pk_mul_f32 v[58:59], v[58:59], v[168:169]
	v_pk_mul_f32 v[48:49], v[48:49], v[168:169]
	v_pk_mul_f32 v[50:51], v[50:51], v[168:169]
	v_exp_f32_e32 v56, v56
	v_exp_f32_e32 v57, v57
	v_exp_f32_e32 v58, v58
	v_exp_f32_e32 v59, v59
	v_exp_f32_e32 v48, v48
	v_exp_f32_e32 v49, v49
	v_exp_f32_e32 v50, v50
	v_exp_f32_e32 v51, v51
	v_add_u32_e32 v186, 0x80, v144
	v_pk_add_f32 v[56:57], v[56:57], v[170:171]
	v_pk_add_f32 v[58:59], v[58:59], v[170:171]
	v_pk_add_f32 v[48:49], v[48:49], v[170:171]
	v_pk_add_f32 v[50:51], v[50:51], v[170:171]
	v_rcp_f32_e32 v56, v56
	v_rcp_f32_e32 v57, v57
	v_rcp_f32_e32 v58, v58
	v_rcp_f32_e32 v59, v59
	v_rcp_f32_e32 v48, v48
	v_rcp_f32_e32 v49, v49
	v_rcp_f32_e32 v50, v50
	v_rcp_f32_e32 v51, v51
	v_mad_i64_i32 v[182:183], s[0:1], v186, s80, v[138:139]
	s_nop 0
	v_pk_mul_f32 v[60:61], v[60:61], v[56:57]
	v_pk_mul_f32 v[62:63], v[62:63], v[58:59]
	v_pk_mul_f32 v[52:53], v[52:53], v[48:49]
	v_pk_mul_f32 v[54:55], v[54:55], v[50:51]
	v_lshl_add_u64 v[184:185], v[182:183], 0, v[180:181]
	v_cvt_pk_bf16_f32 v172, v60, v61
	v_cvt_pk_bf16_f32 v173, v62, v63
	v_cvt_pk_bf16_f32 v174, v52, v53
	v_cvt_pk_bf16_f32 v175, v54, v55
	global_store_dwordx4 v[184:185], v[172:175], off
	v_pk_mul_f32 v[44:45], v[44:45], v[40:41]
	v_pk_mul_f32 v[46:47], v[46:47], v[42:43]
	v_pk_mul_f32 v[36:37], v[36:37], v[32:33]
	v_pk_mul_f32 v[38:39], v[38:39], v[34:35]
	v_pk_mul_f32 v[40:41], v[40:41], v[168:169]
	v_pk_mul_f32 v[42:43], v[42:43], v[168:169]
	v_pk_mul_f32 v[32:33], v[32:33], v[168:169]
	v_pk_mul_f32 v[34:35], v[34:35], v[168:169]
	v_exp_f32_e32 v40, v40
	v_exp_f32_e32 v41, v41
	v_exp_f32_e32 v42, v42
	v_exp_f32_e32 v43, v43
	v_exp_f32_e32 v32, v32
	v_exp_f32_e32 v33, v33
	v_exp_f32_e32 v34, v34
	v_exp_f32_e32 v35, v35
	v_add_u32_e32 v186, 0x90, v144
	v_pk_add_f32 v[40:41], v[40:41], v[170:171]
	v_pk_add_f32 v[42:43], v[42:43], v[170:171]
	v_pk_add_f32 v[32:33], v[32:33], v[170:171]
	v_pk_add_f32 v[34:35], v[34:35], v[170:171]
	v_rcp_f32_e32 v40, v40
	v_rcp_f32_e32 v41, v41
	v_rcp_f32_e32 v42, v42
	v_rcp_f32_e32 v43, v43
	v_rcp_f32_e32 v32, v32
	v_rcp_f32_e32 v33, v33
	v_rcp_f32_e32 v34, v34
	v_rcp_f32_e32 v35, v35
	v_mad_i64_i32 v[182:183], s[0:1], v186, s80, v[138:139]
	s_nop 0
	v_pk_mul_f32 v[44:45], v[44:45], v[40:41]
	v_pk_mul_f32 v[46:47], v[46:47], v[42:43]
	v_pk_mul_f32 v[36:37], v[36:37], v[32:33]
	v_pk_mul_f32 v[38:39], v[38:39], v[34:35]
	v_lshl_add_u64 v[184:185], v[182:183], 0, v[180:181]
	v_cvt_pk_bf16_f32 v176, v44, v45
	v_cvt_pk_bf16_f32 v177, v46, v47
	v_cvt_pk_bf16_f32 v178, v36, v37
	v_cvt_pk_bf16_f32 v179, v38, v39
	global_store_dwordx4 v[184:185], v[176:179], off
	v_pk_mul_f32 v[28:29], v[28:29], v[24:25]
	v_pk_mul_f32 v[30:31], v[30:31], v[26:27]
	v_pk_mul_f32 v[20:21], v[20:21], v[16:17]
	v_pk_mul_f32 v[22:23], v[22:23], v[18:19]
	v_pk_mul_f32 v[24:25], v[24:25], v[168:169]
	v_pk_mul_f32 v[26:27], v[26:27], v[168:169]
	v_pk_mul_f32 v[16:17], v[16:17], v[168:169]
	v_pk_mul_f32 v[18:19], v[18:19], v[168:169]
	v_exp_f32_e32 v24, v24
	v_exp_f32_e32 v25, v25
	v_exp_f32_e32 v26, v26
	v_exp_f32_e32 v27, v27
	v_exp_f32_e32 v16, v16
	v_exp_f32_e32 v17, v17
	v_exp_f32_e32 v18, v18
	v_exp_f32_e32 v19, v19
	v_add_u32_e32 v186, 0xa0, v144
	v_pk_add_f32 v[24:25], v[24:25], v[170:171]
	v_pk_add_f32 v[26:27], v[26:27], v[170:171]
	v_pk_add_f32 v[16:17], v[16:17], v[170:171]
	v_pk_add_f32 v[18:19], v[18:19], v[170:171]
	v_rcp_f32_e32 v24, v24
	v_rcp_f32_e32 v25, v25
	v_rcp_f32_e32 v26, v26
	v_rcp_f32_e32 v27, v27
	v_rcp_f32_e32 v16, v16
	v_rcp_f32_e32 v17, v17
	v_rcp_f32_e32 v18, v18
	v_rcp_f32_e32 v19, v19
	v_mad_i64_i32 v[182:183], s[0:1], v186, s80, v[138:139]
	s_nop 0
	v_pk_mul_f32 v[28:29], v[28:29], v[24:25]
	v_pk_mul_f32 v[30:31], v[30:31], v[26:27]
	v_pk_mul_f32 v[20:21], v[20:21], v[16:17]
	v_pk_mul_f32 v[22:23], v[22:23], v[18:19]
	v_lshl_add_u64 v[184:185], v[182:183], 0, v[180:181]
	v_cvt_pk_bf16_f32 v172, v28, v29
	v_cvt_pk_bf16_f32 v173, v30, v31
	v_cvt_pk_bf16_f32 v174, v20, v21
	v_cvt_pk_bf16_f32 v175, v22, v23
	global_store_dwordx4 v[184:185], v[172:175], off
	v_pk_mul_f32 v[12:13], v[12:13], v[8:9]
	v_pk_mul_f32 v[14:15], v[14:15], v[10:11]
	v_pk_mul_f32 v[4:5], v[4:5], v[0:1]
	v_pk_mul_f32 v[6:7], v[6:7], v[2:3]
	v_pk_mul_f32 v[8:9], v[8:9], v[168:169]
	v_pk_mul_f32 v[10:11], v[10:11], v[168:169]
	v_pk_mul_f32 v[0:1], v[0:1], v[168:169]
	v_pk_mul_f32 v[2:3], v[2:3], v[168:169]
	v_exp_f32_e32 v8, v8
	v_exp_f32_e32 v9, v9
	v_exp_f32_e32 v10, v10
	v_exp_f32_e32 v11, v11
	v_exp_f32_e32 v0, v0
	v_exp_f32_e32 v1, v1
	v_exp_f32_e32 v2, v2
	v_exp_f32_e32 v3, v3
	v_add_u32_e32 v186, 0xb0, v144
	v_pk_add_f32 v[8:9], v[8:9], v[170:171]
	v_pk_add_f32 v[10:11], v[10:11], v[170:171]
	v_pk_add_f32 v[0:1], v[0:1], v[170:171]
	v_pk_add_f32 v[2:3], v[2:3], v[170:171]
	v_rcp_f32_e32 v8, v8
	v_rcp_f32_e32 v9, v9
	v_rcp_f32_e32 v10, v10
	v_rcp_f32_e32 v11, v11
	v_rcp_f32_e32 v0, v0
	v_rcp_f32_e32 v1, v1
	v_rcp_f32_e32 v2, v2
	v_rcp_f32_e32 v3, v3
	v_mad_i64_i32 v[182:183], s[0:1], v186, s80, v[138:139]
	s_nop 0
	v_pk_mul_f32 v[12:13], v[12:13], v[8:9]
	v_pk_mul_f32 v[14:15], v[14:15], v[10:11]
	v_pk_mul_f32 v[4:5], v[4:5], v[0:1]
	v_pk_mul_f32 v[6:7], v[6:7], v[2:3]
	v_lshl_add_u64 v[184:185], v[182:183], 0, v[180:181]
	v_cvt_pk_bf16_f32 v176, v12, v13
	v_cvt_pk_bf16_f32 v177, v14, v15
	v_cvt_pk_bf16_f32 v178, v4, v5
	v_cvt_pk_bf16_f32 v179, v6, v7
	global_store_dwordx4 v[184:185], v[176:179], off
	s_mov_b64 s[0:1], -1
	s_and_b64 vcc, exec, s[4:5]
	s_cbranch_vccnz .LBB0_831
	s_andn2_b64 vcc, exec, s[16:17]
	s_cbranch_vccnz .LBB0_830
	s_barrier
	s_branch .LBB0_830
